# P0: the 512 extra RMSNorm rows are taken by CUs 128-191 instead of CUs 0-63 (which already carry an 11th weight-transposition item)
# speedup vs baseline: 1.0013x; 1.0013x over previous
; __device__ __forceinline__ void phase_prologue(const Args& A, LAS unsigned char* lds, int gw, int NGW, int wave, int lane) {
;     ...
;     const float* x = A.in[0]; const float* mem = A.in[1];
;     bf16* H = (bf16*)(ws + WS_H); bf16* MEMN = (bf16*)(ws + WS_MEMN);
;     for (int m = gw; m < M + 512; m += 2 * NGW) {
;         const int m2 = m + NGW; const bool has2 = m2 < M + 512;
;         const float* r1 = m < M ? x + (size_t)m * DMODEL : mem + (size_t)(m - M) * DMODEL; const float* g1 = m < M ? A.in[2] : A.in[15]; bf16* o1 = m < M ? H + (size_t)m * DMODEL : MEMN + (size_t)(m - M) * DMODEL;
;         const int mb = has2 ? m2 : m;
;         const float* r2 = mb < M ? x + (size_t)mb * DMODEL : mem + (size_t)(mb - M) * DMODEL; const float* g2 = mb < M ? A.in[2] : A.in[15]; bf16* o2 = mb < M ? H + (size_t)mb * DMODEL : MEMN + (size_t)(mb - M) * DMODEL;
.LBB0_81:
	s_cmpk_lg_i32 s70, 0x100
	s_cbranch_scc1 .Lp0_noswap
	s_xor_b32 s31, s31, 0x400
